# stack5 + diff-attention steady loop: LDS-DMA pieces issued inside the PV phase, waves 0-3 after PV MFMAs 2/4/6 and waves 4-7 after 10/12/14, instead of in the MFMA-free block between the phases
# speedup vs baseline: 1.0059x; 1.0023x over previous
; #define WAIT_BAR(N) asm volatile("s_waitcnt vmcnt(" #N ") lgkmcnt(0)\n\ts_barrier":::"memory")
;   #define RESC() do{ if(resc){ asm volatile("s_waitcnt lgkmcnt(0)":::"memory"); \
;       _Pragma("unroll") for(int d_=0;d_<2;++d_) _Pragma("unroll") for(int r=0;r<16;++r)o[d_][r]*=wsf[crow(r,hi)]; } }while(0)
;   #define ROT() do{sl_prev=sl_cur;sl_cur=sl_next;sl_next=(sl_next==(NSLOT-1)*SLOTB)?0:sl_next+SLOTB;}while(0)
; #define WAIT_BAR(N) asm volatile("s_waitcnt vmcnt(" #N ") lgkmcnt(0)\n\ts_barrier":::"memory")
;   #define RESC() do{ if(resc){ asm volatile("s_waitcnt lgkmcnt(0)":::"memory"); \
;       _Pragma("unroll") for(int d_=0;d_<4;++d_) _Pragma("unroll") for(int r=0;r<16;++r)o[d_][r]*=wsf[crow(r,hi)]; } }while(0)
;   #define ROT() do{sl_prev=sl_cur;sl_cur=sl_next;sl_next=(sl_next==(NSLOT-1)*SLOTB)?0:sl_next+SLOTB;}while(0)
; template<int THRL,bool BIAS> __device__ __forceinline__ void attn_unit(int b,int qb,const bf16*Q,const bf16*__restrict__ K,const bf16*__restrict__ V,bf16*O,const float*__restrict__ biasg,char*shm,const int tid_in,const bool comb,const bf16*O0,const float lam,const float osc,const float*__restrict__ ...
;     ...
;   int t=1;
;     ...
;   for(;t+5<NT;t+=2){
;     STEP(pB0,pB1,pA0,pA1,t,true,true,true);     WAIT_BAR(3); RESC(); ROT();
.LBB0_281:
	s_cmp_ge_u32 s83, 0x100
	s_cselect_b64 vcc, -1, 0
	s_waitcnt lgkmcnt(10)
	v_mfma_f32_32x32x16_bf16 v[64:79], v[188:191], v[2:5], v[64:79]
	v_exp_f32_e32 v144, v144
	v_exp_f32_e32 v145, v145
	s_waitcnt lgkmcnt(8)
	v_mfma_f32_32x32x16_bf16 v[48:63], v[188:191], v[6:9], v[48:63]
	v_exp_f32_e32 v146, v146
	v_exp_f32_e32 v147, v147
	s_cbranch_vccnz .Ldsp_1A0
	s_add_i32 m0, s78, s64
	v_lshl_add_u64 v[228:229], v[14:15], 0, s[56:57]
	global_load_lds_dwordx4 v[228:229], off
.Ldsp_1A0:
	v_add_u32_e32 v108, s76, v225
	ds_read_b128 v[96:99], v108
	ds_read_b128 v[10:13], v108 offset:512
	s_waitcnt lgkmcnt(8)
	v_mfma_f32_32x32x16_bf16 v[32:47], v[188:191], v[100:103], v[32:47]
	v_exp_f32_e32 v148, v148
	v_exp_f32_e32 v149, v149
	ds_read_b64_tr_b16 v[100:101], v0 offset:33792
	ds_read_b64_tr_b16 v[102:103], v0 offset:34304
	s_waitcnt lgkmcnt(8)
	v_mfma_f32_32x32x16_bf16 v[16:31], v[188:191], v[104:107], v[16:31]
	v_exp_f32_e32 v150, v150
	v_exp_f32_e32 v151, v151
	s_cbranch_vccnz .Ldsp_1A1
	s_lshl_b32 m0, s76, 1
	s_add_i32 m0, m0, s63
	v_lshl_add_u64 v[228:229], v[208:209], 0, s[48:49]
	global_load_lds_dwordx4 v[228:229], off
.Ldsp_1A1:
	ds_read_b128 v[204:207], v108 offset:2048
	ds_read_b128 v[192:195], v108 offset:2560
	ds_read_b64_tr_b16 v[104:105], v0 offset:37888
	ds_read_b64_tr_b16 v[106:107], v0 offset:38400
	s_waitcnt lgkmcnt(10)
	v_mfma_f32_32x32x16_bf16 v[64:79], v[180:183], v[112:115], v[64:79]
	v_exp_f32_e32 v152, v152
	v_exp_f32_e32 v153, v153
	ds_read_b64_tr_b16 v[112:113], v0 offset:26624
	ds_read_b64_tr_b16 v[114:115], v0 offset:27136
	s_waitcnt lgkmcnt(10)
	v_mfma_f32_32x32x16_bf16 v[48:63], v[180:183], v[116:119], v[48:63]
	v_exp_f32_e32 v154, v154
	v_exp_f32_e32 v155, v155
	s_cbranch_vccnz .Ldsp_1A2
	s_addk_i32 m0, 0x2000
	v_lshl_add_u64 v[228:229], v[210:211], 0, s[48:49]
	global_load_lds_dwordx4 v[228:229], off
.Ldsp_1A2:
	ds_read_b128 v[200:203], v108 offset:4096
	ds_read_b128 v[6:9], v108 offset:4608
	ds_read_b64_tr_b16 v[116:117], v0 offset:30720
	ds_read_b64_tr_b16 v[118:119], v0 offset:31232
	s_waitcnt lgkmcnt(10)
	v_mfma_f32_32x32x16_bf16 v[32:47], v[180:183], v[100:103], v[32:47]
	v_exp_f32_e32 v156, v156
	v_exp_f32_e32 v157, v157
	ds_read_b64_tr_b16 v[100:101], v0 offset:34816
	ds_read_b64_tr_b16 v[102:103], v0 offset:35328
	s_waitcnt lgkmcnt(8)
	v_mfma_f32_32x32x16_bf16 v[16:31], v[180:183], v[104:107], v[16:31]
	v_exp_f32_e32 v158, v158
	v_exp_f32_e32 v159, v159
	ds_read_b128 v[196:199], v108 offset:6144
	ds_read_b128 v[2:5], v108 offset:6656
	ds_read_b64_tr_b16 v[104:105], v0 offset:38912
	ds_read_b64_tr_b16 v[106:107], v0 offset:39424
	s_waitcnt lgkmcnt(10)
	v_mfma_f32_32x32x16_bf16 v[64:79], v[168:171], v[112:115], v[64:79]
	v_exp_f32_e32 v128, v128
	v_exp_f32_e32 v129, v129
	ds_read_b64_tr_b16 v[112:113], v0 offset:27648
	ds_read_b64_tr_b16 v[114:115], v0 offset:28160
	s_waitcnt lgkmcnt(8)
	v_mfma_f32_32x32x16_bf16 v[48:63], v[168:171], v[116:119], v[48:63]
	v_exp_f32_e32 v130, v130
	v_exp_f32_e32 v131, v131
	s_cbranch_vccz .Ldsp_1B0
	s_add_i32 m0, s78, s64
	v_lshl_add_u64 v[228:229], v[14:15], 0, s[56:57]
	global_load_lds_dwordx4 v[228:229], off
.Ldsp_1B0:
	ds_read_b64_tr_b16 v[116:117], v0 offset:31744
	ds_read_b64_tr_b16 v[118:119], v0 offset:32256
	s_waitcnt lgkmcnt(8)
	v_mfma_f32_32x32x16_bf16 v[32:47], v[168:171], v[100:103], v[32:47]
	v_exp_f32_e32 v132, v132
	v_exp_f32_e32 v133, v133
	ds_read_b64_tr_b16 v[100:101], v0 offset:35840
	ds_read_b64_tr_b16 v[102:103], v0 offset:36352
	s_waitcnt lgkmcnt(6)
	v_mfma_f32_32x32x16_bf16 v[16:31], v[168:171], v[104:107], v[16:31]
	v_exp_f32_e32 v134, v134
	v_exp_f32_e32 v135, v135
	s_cbranch_vccz .Ldsp_1B1
	s_lshl_b32 m0, s76, 1
	s_add_i32 m0, m0, s63
	v_lshl_add_u64 v[228:229], v[208:209], 0, s[48:49]
	global_load_lds_dwordx4 v[228:229], off
.Ldsp_1B1:
	ds_read_b64_tr_b16 v[104:105], v0 offset:39936
	ds_read_b64_tr_b16 v[106:107], v0 offset:40448
	s_waitcnt lgkmcnt(6)
	v_mfma_f32_32x32x16_bf16 v[64:79], v[160:163], v[112:115], v[64:79]
	v_exp_f32_e32 v136, v136
	v_exp_f32_e32 v137, v137
	s_waitcnt lgkmcnt(4)
	v_mfma_f32_32x32x16_bf16 v[48:63], v[160:163], v[116:119], v[48:63]
	v_exp_f32_e32 v138, v138
	v_exp_f32_e32 v139, v139
	s_cbranch_vccz .Ldsp_1B2
	s_addk_i32 m0, 0x2000
	v_lshl_add_u64 v[228:229], v[210:211], 0, s[48:49]
	global_load_lds_dwordx4 v[228:229], off
.Ldsp_1B2:
	s_waitcnt lgkmcnt(2)
	v_mfma_f32_32x32x16_bf16 v[32:47], v[160:163], v[100:103], v[32:47]
	v_exp_f32_e32 v140, v140
	v_exp_f32_e32 v141, v141
	s_waitcnt lgkmcnt(0)
	v_mfma_f32_32x32x16_bf16 v[16:31], v[160:163], v[104:107], v[16:31]
	v_exp_f32_e32 v142, v142
	v_exp_f32_e32 v143, v143
	s_waitcnt vmcnt(3) lgkmcnt(0)
	s_barrier
	s_andn2_b64 vcc, exec, s[72:73]
	v_add_u32_e32 v0, s62, v230
	s_cbranch_vccnz .LBB0_283
	s_waitcnt lgkmcnt(0)
	ds_read_b128 v[100:103], v0 offset:96
	ds_read_b128 v[104:107], v0 offset:64
	ds_read_b128 v[108:111], v0 offset:32
	ds_read_b128 v[112:115], v0
	s_waitcnt lgkmcnt(3)
	v_pk_mul_f32 v[76:77], v[76:77], v[100:101]
	s_waitcnt lgkmcnt(2)
	v_pk_mul_f32 v[72:73], v[72:73], v[104:105]
	s_waitcnt lgkmcnt(1)
	v_pk_mul_f32 v[68:69], v[68:69], v[108:109]
	v_pk_mul_f32 v[78:79], v[78:79], v[102:103]
	v_pk_mul_f32 v[74:75], v[74:75], v[106:107]
	v_pk_mul_f32 v[70:71], v[70:71], v[110:111]
	s_waitcnt lgkmcnt(0)
	v_pk_mul_f32 v[66:67], v[66:67], v[114:115]
	v_pk_mul_f32 v[64:65], v[64:65], v[112:113]
	v_pk_mul_f32 v[60:61], v[60:61], v[100:101]
	v_pk_mul_f32 v[56:57], v[56:57], v[104:105]
	v_pk_mul_f32 v[52:53], v[52:53], v[108:109]
	v_pk_mul_f32 v[62:63], v[62:63], v[102:103]
	v_pk_mul_f32 v[58:59], v[58:59], v[106:107]
	v_pk_mul_f32 v[54:55], v[54:55], v[110:111]
	v_pk_mul_f32 v[50:51], v[50:51], v[114:115]
	v_pk_mul_f32 v[48:49], v[48:49], v[112:113]
	v_pk_mul_f32 v[44:45], v[44:45], v[100:101]
	v_pk_mul_f32 v[40:41], v[40:41], v[104:105]
	v_pk_mul_f32 v[36:37], v[36:37], v[108:109]
	v_pk_mul_f32 v[46:47], v[46:47], v[102:103]
	v_pk_mul_f32 v[42:43], v[42:43], v[106:107]
	v_pk_mul_f32 v[38:39], v[38:39], v[110:111]
	v_pk_mul_f32 v[34:35], v[34:35], v[114:115]
	v_pk_mul_f32 v[32:33], v[32:33], v[112:113]
	v_pk_mul_f32 v[28:29], v[28:29], v[100:101]
	v_pk_mul_f32 v[24:25], v[24:25], v[104:105]
	v_pk_mul_f32 v[20:21], v[20:21], v[108:109]
	v_pk_mul_f32 v[30:31], v[30:31], v[102:103]
	v_pk_mul_f32 v[26:27], v[26:27], v[106:107]
	v_pk_mul_f32 v[22:23], v[22:23], v[110:111]
	v_pk_mul_f32 v[18:19], v[18:19], v[114:115]
	v_pk_mul_f32 v[16:17], v[16:17], v[112:113]

; #define WAIT_BAR(N) asm volatile("s_waitcnt vmcnt(" #N ") lgkmcnt(0)\n\ts_barrier":::"memory")
;   #define RESC() do{ if(resc){ asm volatile("s_waitcnt lgkmcnt(0)":::"memory"); \
;       _Pragma("unroll") for(int d_=0;d_<2;++d_) _Pragma("unroll") for(int r=0;r<16;++r)o[d_][r]*=wsf[crow(r,hi)]; } }while(0)
;   #define ROT() do{sl_prev=sl_cur;sl_cur=sl_next;sl_next=(sl_next==(NSLOT-1)*SLOTB)?0:sl_next+SLOTB;}while(0)
; #define WAIT_BAR(N) asm volatile("s_waitcnt vmcnt(" #N ") lgkmcnt(0)\n\ts_barrier":::"memory")
;   #define RESC() do{ if(resc){ asm volatile("s_waitcnt lgkmcnt(0)":::"memory"); \
;       _Pragma("unroll") for(int d_=0;d_<4;++d_) _Pragma("unroll") for(int r=0;r<16;++r)o[d_][r]*=wsf[crow(r,hi)]; } }while(0)
;   #define ROT() do{sl_prev=sl_cur;sl_cur=sl_next;sl_next=(sl_next==(NSLOT-1)*SLOTB)?0:sl_next+SLOTB;}while(0)
; template<int THRL,bool BIAS> __device__ __forceinline__ void attn_unit(int b,int qb,const bf16*Q,const bf16*__restrict__ K,const bf16*__restrict__ V,bf16*O,const float*__restrict__ biasg,char*shm,const int tid_in,const bool comb,const bf16*O0,const float lam,const float osc,const float*__restrict__ ...
;     ...
;   int t=1;
;     ...
;   for(;t+5<NT;t+=2){
;     STEP(pB0,pB1,pA0,pA1,t,true,true,true);     WAIT_BAR(3); RESC(); ROT();
.LBB0_284:
	s_cmp_ge_u32 s83, 0x100
	s_cselect_b64 vcc, -1, 0
	s_waitcnt lgkmcnt(10)
	v_mfma_f32_32x32x16_bf16 v[64:79], v[188:191], v[6:9], v[64:79]
	v_exp_f32_e32 v112, v112
	v_exp_f32_e32 v113, v113
	s_waitcnt lgkmcnt(8)
	v_mfma_f32_32x32x16_bf16 v[48:63], v[188:191], v[10:13], v[48:63]
	v_exp_f32_e32 v114, v114
	v_exp_f32_e32 v115, v115
	s_cbranch_vccnz .Ldsp_2A0
	s_add_i32 m0, s76, s64
	v_lshl_add_u64 v[228:229], v[14:15], 0, s[52:53]
	global_load_lds_dwordx4 v[228:229], off
.Ldsp_2A0:
	v_add_u32_e32 v10, s87, v225
	ds_read_b128 v[220:223], v10
	ds_read_b128 v[212:215], v10 offset:512
	s_waitcnt lgkmcnt(8)
	v_mfma_f32_32x32x16_bf16 v[32:47], v[188:191], v[144:147], v[32:47]
	v_exp_f32_e32 v116, v116
	v_exp_f32_e32 v117, v117
	ds_read_b64_tr_b16 v[144:145], v233 offset:33792
	ds_read_b64_tr_b16 v[146:147], v233 offset:34304
	s_waitcnt lgkmcnt(8)
	v_mfma_f32_32x32x16_bf16 v[16:31], v[188:191], v[148:151], v[16:31]
	v_exp_f32_e32 v118, v118
	v_exp_f32_e32 v119, v119
	s_cbranch_vccnz .Ldsp_2A1
	s_lshl_b32 m0, s87, 1
	s_add_i32 m0, m0, s63
	v_lshl_add_u64 v[228:229], v[236:237], 0, s[6:7]
	v_lshl_add_u64 v[228:229], v[228:229], 0, s[50:51]
	global_load_lds_dwordx4 v[228:229], off
.Ldsp_2A1:
	ds_read_b128 v[216:219], v10 offset:2048
	ds_read_b128 v[204:207], v10 offset:2560
	ds_read_b64_tr_b16 v[148:149], v233 offset:37888
	ds_read_b64_tr_b16 v[150:151], v233 offset:38400
	s_waitcnt lgkmcnt(10)
	v_mfma_f32_32x32x16_bf16 v[64:79], v[180:183], v[152:155], v[64:79]
	v_exp_f32_e32 v120, v120
	v_exp_f32_e32 v121, v121
	ds_read_b64_tr_b16 v[152:153], v233 offset:26624
	ds_read_b64_tr_b16 v[154:155], v233 offset:27136
	s_waitcnt lgkmcnt(10)
	v_mfma_f32_32x32x16_bf16 v[48:63], v[180:183], v[156:159], v[48:63]
	v_exp_f32_e32 v122, v122
	v_exp_f32_e32 v123, v123
	s_cbranch_vccnz .Ldsp_2A2
	s_addk_i32 m0, 0x2000
	v_lshl_add_u64 v[228:229], v[238:239], 0, s[6:7]
	v_lshl_add_u64 v[228:229], v[228:229], 0, s[50:51]
	global_load_lds_dwordx4 v[228:229], off
.Ldsp_2A2:
	ds_read_b128 v[208:211], v10 offset:4096
	ds_read_b128 v[200:203], v10 offset:4608
	ds_read_b64_tr_b16 v[156:157], v233 offset:30720
	ds_read_b64_tr_b16 v[158:159], v233 offset:31232
	s_waitcnt lgkmcnt(10)
	v_mfma_f32_32x32x16_bf16 v[32:47], v[180:183], v[144:147], v[32:47]
	v_exp_f32_e32 v124, v124
	v_exp_f32_e32 v125, v125
	ds_read_b64_tr_b16 v[144:145], v233 offset:34816
	ds_read_b64_tr_b16 v[146:147], v233 offset:35328
	s_waitcnt lgkmcnt(8)
	v_mfma_f32_32x32x16_bf16 v[16:31], v[180:183], v[148:151], v[16:31]
	v_exp_f32_e32 v126, v126
	v_exp_f32_e32 v127, v127
	ds_read_b128 v[196:199], v10 offset:6144
	ds_read_b128 v[192:195], v10 offset:6656
	ds_read_b64_tr_b16 v[148:149], v233 offset:38912
	ds_read_b64_tr_b16 v[150:151], v233 offset:39424
	s_waitcnt lgkmcnt(10)
	v_mfma_f32_32x32x16_bf16 v[64:79], v[168:171], v[152:155], v[64:79]
	v_exp_f32_e32 v96, v96
	v_exp_f32_e32 v97, v97
	ds_read_b64_tr_b16 v[152:153], v233 offset:27648
	ds_read_b64_tr_b16 v[154:155], v233 offset:28160
	s_waitcnt lgkmcnt(8)
	v_mfma_f32_32x32x16_bf16 v[48:63], v[168:171], v[156:159], v[48:63]
	v_exp_f32_e32 v98, v98
	v_exp_f32_e32 v99, v99
	s_cbranch_vccz .Ldsp_2B0
	s_add_i32 m0, s76, s64
	v_lshl_add_u64 v[228:229], v[14:15], 0, s[52:53]
	global_load_lds_dwordx4 v[228:229], off
.Ldsp_2B0:
	ds_read_b64_tr_b16 v[156:157], v233 offset:31744
	ds_read_b64_tr_b16 v[158:159], v233 offset:32256
	s_waitcnt lgkmcnt(8)
	v_mfma_f32_32x32x16_bf16 v[32:47], v[168:171], v[144:147], v[32:47]
	v_exp_f32_e32 v100, v100
	v_exp_f32_e32 v101, v101
	ds_read_b64_tr_b16 v[144:145], v233 offset:35840
	ds_read_b64_tr_b16 v[146:147], v233 offset:36352
	s_waitcnt lgkmcnt(6)
	v_mfma_f32_32x32x16_bf16 v[16:31], v[168:171], v[148:151], v[16:31]
	v_exp_f32_e32 v102, v102
	v_exp_f32_e32 v103, v103
	s_cbranch_vccz .Ldsp_2B1
	s_lshl_b32 m0, s87, 1
	s_add_i32 m0, m0, s63
	v_lshl_add_u64 v[228:229], v[236:237], 0, s[6:7]
	v_lshl_add_u64 v[228:229], v[228:229], 0, s[50:51]
	global_load_lds_dwordx4 v[228:229], off
.Ldsp_2B1:
	ds_read_b64_tr_b16 v[148:149], v233 offset:39936
	ds_read_b64_tr_b16 v[150:151], v233 offset:40448
	s_waitcnt lgkmcnt(6)
	v_mfma_f32_32x32x16_bf16 v[64:79], v[160:163], v[152:155], v[64:79]
	v_exp_f32_e32 v104, v104
	v_exp_f32_e32 v105, v105
	s_waitcnt lgkmcnt(4)
	v_mfma_f32_32x32x16_bf16 v[48:63], v[160:163], v[156:159], v[48:63]
	v_exp_f32_e32 v106, v106
	v_exp_f32_e32 v107, v107
	s_cbranch_vccz .Ldsp_2B2
	s_addk_i32 m0, 0x2000
	v_lshl_add_u64 v[228:229], v[238:239], 0, s[6:7]
	v_lshl_add_u64 v[228:229], v[228:229], 0, s[50:51]
	global_load_lds_dwordx4 v[228:229], off
.Ldsp_2B2:
	s_waitcnt lgkmcnt(2)
	v_mfma_f32_32x32x16_bf16 v[32:47], v[160:163], v[144:147], v[32:47]
	v_exp_f32_e32 v108, v108
	v_exp_f32_e32 v109, v109
	s_waitcnt lgkmcnt(0)
	v_mfma_f32_32x32x16_bf16 v[16:31], v[160:163], v[148:151], v[16:31]
	v_exp_f32_e32 v110, v110
	v_exp_f32_e32 v111, v111
	s_waitcnt vmcnt(3) lgkmcnt(0)
	s_barrier
	s_andn2_b64 vcc, exec, s[72:73]
	s_cbranch_vccnz .LBB0_286
	s_waitcnt lgkmcnt(0)
	ds_read_b128 v[2:5], v0 offset:96
	ds_read_b128 v[6:9], v0 offset:64
	ds_read_b128 v[10:13], v0 offset:32
	ds_read_b128 v[128:131], v0
	s_waitcnt lgkmcnt(3)
	v_pk_mul_f32 v[76:77], v[76:77], v[2:3]
	s_waitcnt lgkmcnt(2)
	v_pk_mul_f32 v[72:73], v[72:73], v[6:7]
	s_waitcnt lgkmcnt(1)
	v_pk_mul_f32 v[68:69], v[68:69], v[10:11]
	v_pk_mul_f32 v[78:79], v[78:79], v[4:5]
	v_pk_mul_f32 v[74:75], v[74:75], v[8:9]
	v_pk_mul_f32 v[70:71], v[70:71], v[12:13]
	s_waitcnt lgkmcnt(0)
	v_pk_mul_f32 v[66:67], v[66:67], v[130:131]
	v_pk_mul_f32 v[64:65], v[64:65], v[128:129]
	v_pk_mul_f32 v[60:61], v[60:61], v[2:3]
	v_pk_mul_f32 v[56:57], v[56:57], v[6:7]
	v_pk_mul_f32 v[52:53], v[52:53], v[10:11]
	v_pk_mul_f32 v[62:63], v[62:63], v[4:5]
	v_pk_mul_f32 v[58:59], v[58:59], v[8:9]
	v_pk_mul_f32 v[54:55], v[54:55], v[12:13]
	v_pk_mul_f32 v[50:51], v[50:51], v[130:131]
	v_pk_mul_f32 v[48:49], v[48:49], v[128:129]
	v_pk_mul_f32 v[44:45], v[44:45], v[2:3]
	v_pk_mul_f32 v[40:41], v[40:41], v[6:7]
	v_pk_mul_f32 v[36:37], v[36:37], v[10:11]
	v_pk_mul_f32 v[46:47], v[46:47], v[4:5]
	v_pk_mul_f32 v[42:43], v[42:43], v[8:9]
	v_pk_mul_f32 v[38:39], v[38:39], v[12:13]
	v_pk_mul_f32 v[34:35], v[34:35], v[130:131]
	v_pk_mul_f32 v[32:33], v[32:33], v[128:129]
	v_pk_mul_f32 v[28:29], v[28:29], v[2:3]
	v_pk_mul_f32 v[24:25], v[24:25], v[6:7]
	v_pk_mul_f32 v[20:21], v[20:21], v[10:11]
	v_pk_mul_f32 v[30:31], v[30:31], v[4:5]
	v_pk_mul_f32 v[26:27], v[26:27], v[8:9]
	v_pk_mul_f32 v[22:23], v[22:23], v[12:13]
	v_pk_mul_f32 v[18:19], v[18:19], v[130:131]
	v_pk_mul_f32 v[16:17], v[16:17], v[128:129]
